# gate/up epilogue: store addresses of groups 1-7 derived from group 0 by one 64-bit add (row pitch) instead of a 64-bit multiply each
# baseline (speedup 1.0000x reference)
.LBB0_380:
	v_mad_u64_u32 v[144:145], s[48:49], s82, v140, 0
	v_readlane_b32 s48, v232, 2
	s_waitcnt lgkmcnt(0)
	v_lshl_or_b32 v142, s69, 7, v148
	v_add3_u32 v145, v145, v150, v151
	v_readlane_b32 s49, v232, 3
	v_ashrrev_i32_e32 v143, 31, v142
	v_pk_mul_f32 v[120:121], v[120:121], v[128:129]
	v_lshl_add_u64 v[144:145], v[144:145], 1, s[48:49]
	s_lshl_b64 s[48:49], s[82:83], 5
	v_pk_mul_f32 v[118:119], v[118:119], v[126:127]
	v_pk_mul_f32 v[124:125], v[116:117], v[124:125]
	v_pk_mul_f32 v[116:117], v[114:115], v[122:123]
	v_lshl_add_u64 v[144:145], v[142:143], 1, v[144:145]
	v_cvt_pk_bf16_f32 v114, v118, v119
	v_cvt_pk_bf16_f32 v115, v120, v121
	v_cvt_pk_bf16_f32 v116, v116, v117
	v_cvt_pk_bf16_f32 v117, v124, v125
	s_and_b64 vcc, exec, s[42:43]
	global_store_dwordx4 v[144:145], v[114:117], off
	s_cbranch_vccnz .LBB0_382
	s_nop 0
	v_mul_f32_e32 v115, 0xbfb8aa3b, v106
	v_exp_f32_e32 v115, v115
	v_mul_f32_e32 v114, 0xbfb8aa3b, v110
	v_exp_f32_e32 v114, v114
	v_mul_f32_e32 v119, 0xbfb8aa3b, v108
	v_add_f32_e32 v115, 1.0, v115
	v_rcp_f32_e32 v116, v115
	v_mul_f32_e32 v115, 0xbfb8aa3b, v111
	v_exp_f32_e32 v115, v115
	v_add_f32_e32 v114, 1.0, v114
	v_exp_f32_e32 v119, v119
	v_rcp_f32_e32 v114, v114
	v_add_f32_e32 v115, 1.0, v115
	v_rcp_f32_e32 v115, v115
	v_add_f32_e32 v119, 1.0, v119
	v_mul_f32_e32 v117, 0xbfb8aa3b, v107
	v_mul_f32_e32 v118, 0xbfb8aa3b, v112
	v_rcp_f32_e32 v120, v119
	v_mul_f32_e32 v119, 0xbfb8aa3b, v113
	v_pk_mul_f32 v[110:111], v[110:111], v[114:115]
	v_mul_f32_e32 v114, 0xbfb8aa3b, v109
	v_exp_f32_e32 v117, v117
	v_exp_f32_e32 v118, v118
	v_exp_f32_e32 v119, v119
	v_exp_f32_e32 v114, v114
	v_add_f32_e32 v117, 1.0, v117
	v_add_f32_e32 v118, 1.0, v118
	v_add_f32_e32 v119, 1.0, v119
	v_add_f32_e32 v114, 1.0, v114
	v_rcp_f32_e32 v117, v117
	v_rcp_f32_e32 v118, v118
	v_rcp_f32_e32 v119, v119
	v_rcp_f32_e32 v121, v114
	v_pk_mul_f32 v[106:107], v[106:107], v[116:117]
	v_pk_mul_f32 v[112:113], v[112:113], v[118:119]
	v_pk_mul_f32 v[108:109], v[108:109], v[120:121]
.LBB0_382:
	s_nop 0
	v_pk_mul_f32 v[104:105], v[104:105], v[112:113]
	v_pk_mul_f32 v[102:103], v[102:103], v[110:111]
	v_pk_mul_f32 v[108:109], v[100:101], v[108:109]
	v_pk_mul_f32 v[100:101], v[98:99], v[106:107]
	v_lshl_add_u64 v[114:115], s[48:49], 0, v[144:145]
	v_cvt_pk_bf16_f32 v98, v102, v103
	v_cvt_pk_bf16_f32 v99, v104, v105
	v_cvt_pk_bf16_f32 v100, v100, v101
	v_cvt_pk_bf16_f32 v101, v108, v109
	s_and_b64 vcc, exec, s[42:43]
	global_store_dwordx4 v[114:115], v[98:101], off
	s_cbranch_vccnz .LBB0_384
	s_nop 0
	v_mul_f32_e32 v99, 0xbfb8aa3b, v88
	v_exp_f32_e32 v99, v99
	v_mul_f32_e32 v98, 0xbfb8aa3b, v92
	v_exp_f32_e32 v98, v98
	v_mul_f32_e32 v103, 0xbfb8aa3b, v90
	v_add_f32_e32 v99, 1.0, v99
	v_rcp_f32_e32 v100, v99
	v_mul_f32_e32 v99, 0xbfb8aa3b, v93
	v_exp_f32_e32 v99, v99
	v_add_f32_e32 v98, 1.0, v98
	v_exp_f32_e32 v103, v103
	v_rcp_f32_e32 v98, v98
	v_add_f32_e32 v99, 1.0, v99
	v_rcp_f32_e32 v99, v99
	v_add_f32_e32 v103, 1.0, v103
	v_mul_f32_e32 v101, 0xbfb8aa3b, v89
	v_mul_f32_e32 v102, 0xbfb8aa3b, v94
	v_rcp_f32_e32 v104, v103
	v_mul_f32_e32 v103, 0xbfb8aa3b, v95
	v_pk_mul_f32 v[92:93], v[92:93], v[98:99]
	v_mul_f32_e32 v98, 0xbfb8aa3b, v91
	v_exp_f32_e32 v101, v101
	v_exp_f32_e32 v102, v102
	v_exp_f32_e32 v103, v103
	v_exp_f32_e32 v98, v98
	v_add_f32_e32 v101, 1.0, v101
	v_add_f32_e32 v102, 1.0, v102
	v_add_f32_e32 v103, 1.0, v103
	v_add_f32_e32 v98, 1.0, v98
	v_rcp_f32_e32 v101, v101
	v_rcp_f32_e32 v102, v102
	v_rcp_f32_e32 v103, v103
	v_rcp_f32_e32 v105, v98
	v_pk_mul_f32 v[88:89], v[88:89], v[100:101]
	v_pk_mul_f32 v[94:95], v[94:95], v[102:103]
	v_pk_mul_f32 v[90:91], v[90:91], v[104:105]
.LBB0_384:
	s_nop 0
	v_pk_mul_f32 v[86:87], v[86:87], v[94:95]
	v_pk_mul_f32 v[84:85], v[84:85], v[92:93]
	v_pk_mul_f32 v[90:91], v[82:83], v[90:91]
	v_pk_mul_f32 v[82:83], v[80:81], v[88:89]
	v_lshl_add_u64 v[98:99], s[48:49], 1, v[144:145]
	v_cvt_pk_bf16_f32 v80, v84, v85
	v_cvt_pk_bf16_f32 v81, v86, v87
	v_cvt_pk_bf16_f32 v82, v82, v83
	v_cvt_pk_bf16_f32 v83, v90, v91
	s_and_b64 vcc, exec, s[42:43]
	global_store_dwordx4 v[98:99], v[80:83], off
	s_cbranch_vccnz .LBB0_386
	s_nop 0
	v_mul_f32_e32 v81, 0xbfb8aa3b, v72
	v_exp_f32_e32 v81, v81
	v_mul_f32_e32 v80, 0xbfb8aa3b, v76
	v_exp_f32_e32 v80, v80
	v_mul_f32_e32 v85, 0xbfb8aa3b, v74
	v_add_f32_e32 v81, 1.0, v81
	v_rcp_f32_e32 v82, v81
	v_mul_f32_e32 v81, 0xbfb8aa3b, v77
	v_exp_f32_e32 v81, v81
	v_add_f32_e32 v80, 1.0, v80
	v_exp_f32_e32 v85, v85
	v_rcp_f32_e32 v80, v80
	v_add_f32_e32 v81, 1.0, v81
	v_rcp_f32_e32 v81, v81
	v_add_f32_e32 v85, 1.0, v85
	v_mul_f32_e32 v83, 0xbfb8aa3b, v73
	v_mul_f32_e32 v84, 0xbfb8aa3b, v78
	v_rcp_f32_e32 v86, v85
	v_mul_f32_e32 v85, 0xbfb8aa3b, v79
	v_pk_mul_f32 v[76:77], v[76:77], v[80:81]
	v_mul_f32_e32 v80, 0xbfb8aa3b, v75
	v_exp_f32_e32 v83, v83
	v_exp_f32_e32 v84, v84
	v_exp_f32_e32 v85, v85
	v_exp_f32_e32 v80, v80
	v_add_f32_e32 v83, 1.0, v83
	v_add_f32_e32 v84, 1.0, v84
	v_add_f32_e32 v85, 1.0, v85
	v_add_f32_e32 v80, 1.0, v80
	v_rcp_f32_e32 v83, v83
	v_rcp_f32_e32 v84, v84
	v_rcp_f32_e32 v85, v85
	v_rcp_f32_e32 v87, v80
	v_pk_mul_f32 v[72:73], v[72:73], v[82:83]
	v_pk_mul_f32 v[78:79], v[78:79], v[84:85]
	v_pk_mul_f32 v[74:75], v[74:75], v[86:87]
.LBB0_386:
	s_nop 0
	v_pk_mul_f32 v[70:71], v[70:71], v[78:79]
	v_pk_mul_f32 v[68:69], v[68:69], v[76:77]
	v_pk_mul_f32 v[74:75], v[66:67], v[74:75]
	v_pk_mul_f32 v[66:67], v[64:65], v[72:73]
	v_lshl_add_u64 v[80:81], s[48:49], 0, v[98:99]
	v_cvt_pk_bf16_f32 v64, v68, v69
	v_cvt_pk_bf16_f32 v65, v70, v71
	v_cvt_pk_bf16_f32 v66, v66, v67
	v_cvt_pk_bf16_f32 v67, v74, v75
	s_and_b64 vcc, exec, s[42:43]
	global_store_dwordx4 v[80:81], v[64:67], off
	s_cbranch_vccnz .LBB0_388
	s_nop 0
	v_mul_f32_e32 v65, 0xbfb8aa3b, v56
	v_exp_f32_e32 v65, v65
	v_mul_f32_e32 v64, 0xbfb8aa3b, v60
	v_exp_f32_e32 v64, v64
	v_mul_f32_e32 v69, 0xbfb8aa3b, v58
	v_add_f32_e32 v65, 1.0, v65
	v_rcp_f32_e32 v66, v65
	v_mul_f32_e32 v65, 0xbfb8aa3b, v61
	v_exp_f32_e32 v65, v65
	v_add_f32_e32 v64, 1.0, v64
	v_exp_f32_e32 v69, v69
	v_rcp_f32_e32 v64, v64
	v_add_f32_e32 v65, 1.0, v65
	v_rcp_f32_e32 v65, v65
	v_add_f32_e32 v69, 1.0, v69
	v_mul_f32_e32 v67, 0xbfb8aa3b, v57
	v_mul_f32_e32 v68, 0xbfb8aa3b, v62
	v_rcp_f32_e32 v70, v69
	v_mul_f32_e32 v69, 0xbfb8aa3b, v63
	v_pk_mul_f32 v[60:61], v[60:61], v[64:65]
	v_mul_f32_e32 v64, 0xbfb8aa3b, v59
	v_exp_f32_e32 v67, v67
	v_exp_f32_e32 v68, v68
	v_exp_f32_e32 v69, v69
	v_exp_f32_e32 v64, v64
	v_add_f32_e32 v67, 1.0, v67
	v_add_f32_e32 v68, 1.0, v68
	v_add_f32_e32 v69, 1.0, v69
	v_add_f32_e32 v64, 1.0, v64
	v_rcp_f32_e32 v67, v67
	v_rcp_f32_e32 v68, v68
	v_rcp_f32_e32 v69, v69
	v_rcp_f32_e32 v71, v64
	v_pk_mul_f32 v[56:57], v[56:57], v[66:67]
	v_pk_mul_f32 v[62:63], v[62:63], v[68:69]
	v_pk_mul_f32 v[58:59], v[58:59], v[70:71]
.LBB0_388:
	s_nop 0
	v_pk_mul_f32 v[54:55], v[54:55], v[62:63]
	v_pk_mul_f32 v[52:53], v[52:53], v[60:61]
	v_pk_mul_f32 v[58:59], v[50:51], v[58:59]
	v_pk_mul_f32 v[50:51], v[48:49], v[56:57]
	v_lshl_add_u64 v[64:65], s[48:49], 3, v[144:145]
	v_cvt_pk_bf16_f32 v48, v52, v53
	v_cvt_pk_bf16_f32 v49, v54, v55
	v_cvt_pk_bf16_f32 v50, v50, v51
	v_cvt_pk_bf16_f32 v51, v58, v59
	s_and_b64 vcc, exec, s[42:43]
	global_store_dwordx4 v[64:65], v[48:51], off
	s_cbranch_vccnz .LBB0_390
	s_nop 0
	v_mul_f32_e32 v49, 0xbfb8aa3b, v40
	v_exp_f32_e32 v49, v49
	v_mul_f32_e32 v48, 0xbfb8aa3b, v44
	v_exp_f32_e32 v48, v48
	v_mul_f32_e32 v53, 0xbfb8aa3b, v42
	v_add_f32_e32 v49, 1.0, v49
	v_rcp_f32_e32 v50, v49
	v_mul_f32_e32 v49, 0xbfb8aa3b, v45
	v_exp_f32_e32 v49, v49
	v_add_f32_e32 v48, 1.0, v48
	v_exp_f32_e32 v53, v53
	v_rcp_f32_e32 v48, v48
	v_add_f32_e32 v49, 1.0, v49
	v_rcp_f32_e32 v49, v49
	v_add_f32_e32 v53, 1.0, v53
	v_mul_f32_e32 v51, 0xbfb8aa3b, v41
	v_mul_f32_e32 v52, 0xbfb8aa3b, v46
	v_rcp_f32_e32 v54, v53
	v_mul_f32_e32 v53, 0xbfb8aa3b, v47
	v_pk_mul_f32 v[44:45], v[44:45], v[48:49]
	v_mul_f32_e32 v48, 0xbfb8aa3b, v43
	v_exp_f32_e32 v51, v51
	v_exp_f32_e32 v52, v52
	v_exp_f32_e32 v53, v53
	v_exp_f32_e32 v48, v48
	v_add_f32_e32 v51, 1.0, v51
	v_add_f32_e32 v52, 1.0, v52
	v_add_f32_e32 v53, 1.0, v53
	v_add_f32_e32 v48, 1.0, v48
	v_rcp_f32_e32 v51, v51
	v_rcp_f32_e32 v52, v52
	v_rcp_f32_e32 v53, v53
	v_rcp_f32_e32 v55, v48
	v_pk_mul_f32 v[40:41], v[40:41], v[50:51]
	v_pk_mul_f32 v[46:47], v[46:47], v[52:53]
	v_pk_mul_f32 v[42:43], v[42:43], v[54:55]
.LBB0_390:
	s_nop 0
	v_pk_mul_f32 v[38:39], v[38:39], v[46:47]
	v_pk_mul_f32 v[36:37], v[36:37], v[44:45]
	v_pk_mul_f32 v[42:43], v[34:35], v[42:43]
	v_pk_mul_f32 v[34:35], v[32:33], v[40:41]
	v_lshl_add_u64 v[48:49], s[48:49], 0, v[64:65]
	v_cvt_pk_bf16_f32 v32, v36, v37
	v_cvt_pk_bf16_f32 v33, v38, v39
	v_cvt_pk_bf16_f32 v34, v34, v35
	v_cvt_pk_bf16_f32 v35, v42, v43
	s_and_b64 vcc, exec, s[42:43]
	global_store_dwordx4 v[48:49], v[32:35], off
	s_cbranch_vccnz .LBB0_392
	s_nop 0
	v_mul_f32_e32 v33, 0xbfb8aa3b, v24
	v_exp_f32_e32 v33, v33
	v_mul_f32_e32 v32, 0xbfb8aa3b, v28
	v_exp_f32_e32 v32, v32
	v_mul_f32_e32 v37, 0xbfb8aa3b, v26
	v_add_f32_e32 v33, 1.0, v33
	v_rcp_f32_e32 v34, v33
	v_mul_f32_e32 v33, 0xbfb8aa3b, v29
	v_exp_f32_e32 v33, v33
	v_add_f32_e32 v32, 1.0, v32
	v_exp_f32_e32 v37, v37
	v_rcp_f32_e32 v32, v32
	v_add_f32_e32 v33, 1.0, v33
	v_rcp_f32_e32 v33, v33
	v_add_f32_e32 v37, 1.0, v37
	v_mul_f32_e32 v35, 0xbfb8aa3b, v25
	v_mul_f32_e32 v36, 0xbfb8aa3b, v30
	v_rcp_f32_e32 v38, v37
	v_mul_f32_e32 v37, 0xbfb8aa3b, v31
	v_pk_mul_f32 v[28:29], v[28:29], v[32:33]
	v_mul_f32_e32 v32, 0xbfb8aa3b, v27
	v_exp_f32_e32 v35, v35
	v_exp_f32_e32 v36, v36
	v_exp_f32_e32 v37, v37
	v_exp_f32_e32 v32, v32
	v_add_f32_e32 v35, 1.0, v35
	v_add_f32_e32 v36, 1.0, v36
	v_add_f32_e32 v37, 1.0, v37
	v_add_f32_e32 v32, 1.0, v32
	v_rcp_f32_e32 v35, v35
	v_rcp_f32_e32 v36, v36
	v_rcp_f32_e32 v37, v37
	v_rcp_f32_e32 v39, v32
	v_pk_mul_f32 v[24:25], v[24:25], v[34:35]
	v_pk_mul_f32 v[30:31], v[30:31], v[36:37]
	v_pk_mul_f32 v[26:27], v[26:27], v[38:39]
.LBB0_392:
	s_nop 0
	v_pk_mul_f32 v[22:23], v[22:23], v[30:31]
	v_pk_mul_f32 v[20:21], v[20:21], v[28:29]
	v_pk_mul_f32 v[26:27], v[18:19], v[26:27]
	v_pk_mul_f32 v[18:19], v[16:17], v[24:25]
	v_lshl_add_u64 v[32:33], s[48:49], 1, v[64:65]
	v_cvt_pk_bf16_f32 v16, v20, v21
	v_cvt_pk_bf16_f32 v17, v22, v23
	v_cvt_pk_bf16_f32 v18, v18, v19
	v_cvt_pk_bf16_f32 v19, v26, v27
	s_and_b64 vcc, exec, s[42:43]
	global_store_dwordx4 v[32:33], v[16:19], off
	s_cbranch_vccnz .LBB0_394
	s_nop 0
	v_mul_f32_e32 v17, 0xbfb8aa3b, v8
	v_exp_f32_e32 v17, v17
	v_mul_f32_e32 v16, 0xbfb8aa3b, v12
	v_exp_f32_e32 v16, v16
	v_mul_f32_e32 v21, 0xbfb8aa3b, v10
	v_add_f32_e32 v17, 1.0, v17
	v_rcp_f32_e32 v18, v17
	v_mul_f32_e32 v17, 0xbfb8aa3b, v13
	v_exp_f32_e32 v17, v17
	v_add_f32_e32 v16, 1.0, v16
	v_exp_f32_e32 v21, v21
	v_rcp_f32_e32 v16, v16
	v_add_f32_e32 v17, 1.0, v17
	v_rcp_f32_e32 v17, v17
	v_add_f32_e32 v21, 1.0, v21
	v_mul_f32_e32 v19, 0xbfb8aa3b, v9
	v_mul_f32_e32 v20, 0xbfb8aa3b, v14
	v_rcp_f32_e32 v22, v21
	v_mul_f32_e32 v21, 0xbfb8aa3b, v15
	v_pk_mul_f32 v[12:13], v[12:13], v[16:17]
	v_mul_f32_e32 v16, 0xbfb8aa3b, v11
	v_exp_f32_e32 v19, v19
	v_exp_f32_e32 v20, v20
	v_exp_f32_e32 v21, v21
	v_exp_f32_e32 v16, v16
	v_add_f32_e32 v19, 1.0, v19
	v_add_f32_e32 v20, 1.0, v20
	v_add_f32_e32 v21, 1.0, v21
	v_add_f32_e32 v16, 1.0, v16
	v_rcp_f32_e32 v19, v19
	v_rcp_f32_e32 v20, v20
	v_rcp_f32_e32 v21, v21
	v_rcp_f32_e32 v23, v16
	v_pk_mul_f32 v[8:9], v[8:9], v[18:19]
	v_pk_mul_f32 v[14:15], v[14:15], v[20:21]
	v_pk_mul_f32 v[10:11], v[10:11], v[22:23]
.LBB0_394:
	s_nop 0
	v_pk_mul_f32 v[6:7], v[6:7], v[14:15]
	v_pk_mul_f32 v[4:5], v[4:5], v[12:13]
	v_pk_mul_f32 v[10:11], v[2:3], v[10:11]
	v_pk_mul_f32 v[2:3], v[0:1], v[8:9]
	v_lshl_add_u64 v[16:17], s[48:49], 0, v[32:33]
	v_cvt_pk_bf16_f32 v0, v4, v5
	v_cvt_pk_bf16_f32 v1, v6, v7
	v_cvt_pk_bf16_f32 v2, v2, v3
	v_cvt_pk_bf16_f32 v3, v10, v11
	global_store_dwordx4 v[16:17], v[0:3], off
	s_and_b64 vcc, exec, s[40:41]
	s_mov_b64 s[40:41], -1
	s_cbranch_vccnz .LBB0_325
